# P10 residual epilogue rewritten like P5/P8: W_down^T rows stored permuted in the P7 conversion so each lane owns 8 contiguous output columns; 16-byte bf16 residual loads double-buffered, adjacent 16-b
# baseline (speedup 1.0000x reference)
.LBB0_1254:
	s_add_i32 s0, s0, s2
	v_add_u32_e32 v8, s0, v159
	v_cmp_gt_i32_e32 vcc, s5, v8
	s_and_saveexec_b64 s[0:1], vcc
	s_cbranch_execz .LBB0_1257
	v_mul_u32_u24_e32 v0, 0x4100, v159
	v_add_u32_e32 v4, 0, v0
	v_lshlrev_b32_e32 v0, 4, v158
	v_and_b32_e32 v2, 0xf0, v0
	v_mov_b32_e32 v3, 0
	v_lshl_add_u64 v[0:1], s[80:81], 0, v[2:3]
	v_add_u32_e32 v5, v4, v2
	v_lshlrev_b32_e32 v2, 3, v158
	v_bfe_u32 v9, v158, 4, 2
	v_bfe_u32 v10, v158, 3, 3
	v_and_b32_e32 v134, 3, v10
	v_and_b32_e32 v135, 4, v10
	v_lshl_or_b32 v134, v135, 2, v134
	v_and_b32_e32 v2, 56, v2
	v_mul_u32_u24_e32 v6, 0x104, v9
	v_mul_u32_u24_e32 v7, 0x104, v2
	v_lshlrev_b32_e32 v2, 1, v2
	v_lshlrev_b32_e32 v11, 2, v10
	v_lshl_add_u64 v[2:3], s[84:85], 0, v[2:3]
	s_mov_b64 s[2:3], 0x3000000
	v_add3_u32 v11, v4, v7, v11
	v_add_u32_e32 v13, v5, v6
	v_lshl_add_u64 v[2:3], v[2:3], 0, s[2:3]
	v_lshlrev_b32_e32 v12, 6, v8
	s_lshl_b32 s6, s4, 6
	s_mov_b64 s[2:3], 0
	v_add_u32_e32 v14, 0x410, v13
	v_add_u32_e32 v15, 0x418, v13
	v_add_u32_e32 v16, 0x820, v13
	v_add_u32_e32 v17, 0x828, v13
	v_add_u32_e32 v18, 0xc30, v13
	v_add_u32_e32 v19, 0xc38, v13
	v_add_u32_e32 v20, 0x1040, v13
	v_add_u32_e32 v21, 0x1048, v13
	v_add_u32_e32 v22, 0x1450, v13
	v_add_u32_e32 v23, 0x1458, v13
	v_add_u32_e32 v24, 0x1860, v13
	v_add_u32_e32 v25, 0x1868, v13
	v_add_u32_e32 v26, 0x1c70, v13
	v_add_u32_e32 v27, 0x1c78, v13
	v_add_u32_e32 v28, 0x2080, v13
	v_add_u32_e32 v29, 0x2088, v13
	v_add_u32_e32 v30, 0x2490, v13
	v_add_u32_e32 v31, 0x2498, v13
	v_add_u32_e32 v32, 0x28a0, v13
	v_add_u32_e32 v33, 0x28a8, v13
	v_add_u32_e32 v34, 0x2cb0, v13
	v_add_u32_e32 v35, 0x2cb8, v13
	v_add_u32_e32 v36, 0x30c0, v13
	v_add_u32_e32 v37, 0x30c8, v13
	v_add_u32_e32 v38, 0x34d0, v13
	v_add_u32_e32 v39, 0x34d8, v13
	v_add_u32_e32 v40, 0x38e0, v13
	v_add_u32_e32 v41, 0x38e8, v13
	v_add_u32_e32 v42, 0x3cf0, v13
	v_add_u32_e32 v43, 0x3cf8, v13
	v_add_u32_e32 v44, 0x400, v11
.LBB0_1256:
	v_ashrrev_i32_e32 v4, 31, v8
	v_lshrrev_b32_e32 v4, 27, v4
	v_add_u32_e32 v4, v8, v4
	v_ashrrev_i32_e32 v4, 5, v4
	v_lshlrev_b32_e32 v5, 11, v4
	v_lshlrev_b32_e32 v4, 6, v4
	v_or_b32_e32 v48, v4, v9
	v_sub_u32_e32 v46, v12, v5
	v_or_b32_e32 v50, 4, v48
	v_or_b32_e32 v52, 8, v48
	v_or_b32_e32 v54, 12, v48
	v_or_b32_e32 v56, 16, v48
	v_or_b32_e32 v58, 20, v48
	v_or_b32_e32 v60, 24, v48
	v_or_b32_e32 v62, 28, v48
	v_or_b32_e32 v64, 32, v48
	v_or_b32_e32 v66, 36, v48
	v_or_b32_e32 v68, 40, v48
	v_or_b32_e32 v70, 44, v48
	v_ashrrev_i32_e32 v47, 31, v46
	v_ashrrev_i32_e32 v49, 31, v48
	v_or_b32_e32 v72, 48, v48
	v_or_b32_e32 v74, 52, v48
	v_or_b32_e32 v76, 56, v48
	v_or_b32_e32 v78, 60, v48
	v_ashrrev_i32_e32 v51, 31, v50
	v_ashrrev_i32_e32 v53, 31, v52
	v_ashrrev_i32_e32 v55, 31, v54
	v_ashrrev_i32_e32 v57, 31, v56
	v_ashrrev_i32_e32 v59, 31, v58
	v_ashrrev_i32_e32 v61, 31, v60
	v_ashrrev_i32_e32 v63, 31, v62
	v_ashrrev_i32_e32 v65, 31, v64
	v_ashrrev_i32_e32 v67, 31, v66
	v_ashrrev_i32_e32 v69, 31, v68
	v_ashrrev_i32_e32 v71, 31, v70
	v_add_u32_e32 v6, v46, v134
	v_lshl_add_u64 v[80:81], v[46:47], 2, v[0:1]
	v_lshlrev_b64 v[46:47], 13, v[48:49]
	v_ashrrev_i32_e32 v73, 31, v72
	v_ashrrev_i32_e32 v75, 31, v74
	v_ashrrev_i32_e32 v77, 31, v76
	v_ashrrev_i32_e32 v79, 31, v78
	v_lshlrev_b64 v[50:51], 13, v[50:51]
	v_lshlrev_b64 v[52:53], 13, v[52:53]
	v_lshlrev_b64 v[54:55], 13, v[54:55]
	v_lshlrev_b64 v[56:57], 13, v[56:57]
	v_lshlrev_b64 v[58:59], 13, v[58:59]
	v_lshlrev_b64 v[60:61], 13, v[60:61]
	v_lshlrev_b64 v[62:63], 13, v[62:63]
	v_lshlrev_b64 v[64:65], 13, v[64:65]
	v_lshlrev_b64 v[66:67], 13, v[66:67]
	v_lshlrev_b64 v[68:69], 13, v[68:69]
	v_lshlrev_b64 v[70:71], 13, v[70:71]
	v_lshl_add_u64 v[46:47], v[80:81], 0, v[46:47]
	v_lshlrev_b64 v[72:73], 13, v[72:73]
	v_lshlrev_b64 v[74:75], 13, v[74:75]
	v_lshlrev_b64 v[76:77], 13, v[76:77]
	v_lshlrev_b64 v[78:79], 13, v[78:79]
	v_lshl_add_u64 v[86:87], v[80:81], 0, v[50:51]
	v_lshl_add_u64 v[88:89], v[80:81], 0, v[52:53]
	v_lshl_add_u64 v[90:91], v[80:81], 0, v[54:55]
	v_lshl_add_u64 v[92:93], v[80:81], 0, v[56:57]
	v_lshl_add_u64 v[94:95], v[80:81], 0, v[58:59]
	v_lshl_add_u64 v[96:97], v[80:81], 0, v[60:61]
	v_lshl_add_u64 v[98:99], v[80:81], 0, v[62:63]
	v_lshl_add_u64 v[100:101], v[80:81], 0, v[64:65]
	v_lshl_add_u64 v[102:103], v[80:81], 0, v[66:67]
	v_lshl_add_u64 v[106:107], v[80:81], 0, v[68:69]
	v_lshl_add_u64 v[108:109], v[80:81], 0, v[70:71]
	global_load_dwordx4 v[46:49], v[46:47], off nt
	v_lshl_add_u64 v[124:125], v[80:81], 0, v[72:73]
	v_lshl_add_u64 v[126:127], v[80:81], 0, v[74:75]
	v_lshl_add_u64 v[128:129], v[80:81], 0, v[76:77]
	v_lshl_add_u64 v[130:131], v[80:81], 0, v[78:79]
	global_load_dwordx4 v[50:53], v[86:87], off nt
	global_load_dwordx4 v[54:57], v[88:89], off nt
	global_load_dwordx4 v[58:61], v[90:91], off nt
	global_load_dwordx4 v[62:65], v[92:93], off nt
	global_load_dwordx4 v[66:69], v[94:95], off nt
	global_load_dwordx4 v[70:73], v[96:97], off nt
	global_load_dwordx4 v[74:77], v[98:99], off nt
	global_load_dwordx4 v[78:81], v[100:101], off nt
	global_load_dwordx4 v[82:85], v[102:103], off nt
	global_load_dwordx4 v[86:89], v[106:107], off nt
	global_load_dwordx4 v[90:93], v[108:109], off nt
	global_load_dwordx4 v[94:97], v[124:125], off nt
	s_nop 0
	global_load_dwordx4 v[98:101], v[126:127], off nt
	global_load_dwordx4 v[102:105], v[128:129], off nt
	global_load_dwordx4 v[106:109], v[130:131], off nt
.Lmy_cv_loop:
	v_add_u32_e32 v132, s4, v8
	v_add_u32_e32 v133, s6, v12
	v_cmp_gt_i32_e32 vcc, s5, v132
	s_cbranch_vccz .Lmy_cv_nonext
	v_ashrrev_i32_e32 v246, 31, v132
	v_lshrrev_b32_e32 v246, 27, v246
	v_add_u32_e32 v246, v132, v246
	v_ashrrev_i32_e32 v246, 5, v246
	v_lshlrev_b32_e32 v247, 11, v246
	v_lshlrev_b32_e32 v246, 6, v246
	v_or_b32_e32 v162, v246, v9
	v_sub_u32_e32 v160, v133, v247
	v_or_b32_e32 v164, 4, v162
	v_or_b32_e32 v166, 8, v162
	v_or_b32_e32 v168, 12, v162
	v_or_b32_e32 v170, 16, v162
	v_or_b32_e32 v172, 20, v162
	v_or_b32_e32 v174, 24, v162
	v_or_b32_e32 v176, 28, v162
	v_or_b32_e32 v178, 32, v162
	v_or_b32_e32 v180, 36, v162
	v_or_b32_e32 v182, 40, v162
	v_or_b32_e32 v184, 44, v162
	v_ashrrev_i32_e32 v161, 31, v160
	v_ashrrev_i32_e32 v163, 31, v162
	v_or_b32_e32 v186, 48, v162
	v_or_b32_e32 v188, 52, v162
	v_or_b32_e32 v190, 56, v162
	v_or_b32_e32 v192, 60, v162
	v_ashrrev_i32_e32 v165, 31, v164
	v_ashrrev_i32_e32 v167, 31, v166
	v_ashrrev_i32_e32 v169, 31, v168
	v_ashrrev_i32_e32 v171, 31, v170
	v_ashrrev_i32_e32 v173, 31, v172
	v_ashrrev_i32_e32 v175, 31, v174
	v_ashrrev_i32_e32 v177, 31, v176
	v_ashrrev_i32_e32 v179, 31, v178
	v_ashrrev_i32_e32 v181, 31, v180
	v_ashrrev_i32_e32 v183, 31, v182
	v_ashrrev_i32_e32 v185, 31, v184
	v_add_u32_e32 v248, v160, v134
	v_lshl_add_u64 v[194:195], v[160:161], 2, v[0:1]
	v_lshlrev_b64 v[160:161], 13, v[162:163]
	v_ashrrev_i32_e32 v187, 31, v186
	v_ashrrev_i32_e32 v189, 31, v188
	v_ashrrev_i32_e32 v191, 31, v190
	v_ashrrev_i32_e32 v193, 31, v192
	v_lshlrev_b64 v[164:165], 13, v[164:165]
	v_lshlrev_b64 v[166:167], 13, v[166:167]
	v_lshlrev_b64 v[168:169], 13, v[168:169]
	v_lshlrev_b64 v[170:171], 13, v[170:171]
	v_lshlrev_b64 v[172:173], 13, v[172:173]
	v_lshlrev_b64 v[174:175], 13, v[174:175]
	v_lshlrev_b64 v[176:177], 13, v[176:177]
	v_lshlrev_b64 v[178:179], 13, v[178:179]
	v_lshlrev_b64 v[180:181], 13, v[180:181]
	v_lshlrev_b64 v[182:183], 13, v[182:183]
	v_lshlrev_b64 v[184:185], 13, v[184:185]
	v_lshl_add_u64 v[160:161], v[194:195], 0, v[160:161]
	v_lshlrev_b64 v[186:187], 13, v[186:187]
	v_lshlrev_b64 v[188:189], 13, v[188:189]
	v_lshlrev_b64 v[190:191], 13, v[190:191]
	v_lshlrev_b64 v[192:193], 13, v[192:193]
	v_lshl_add_u64 v[200:201], v[194:195], 0, v[164:165]
	v_lshl_add_u64 v[202:203], v[194:195], 0, v[166:167]
	v_lshl_add_u64 v[204:205], v[194:195], 0, v[168:169]
	v_lshl_add_u64 v[206:207], v[194:195], 0, v[170:171]
	v_lshl_add_u64 v[208:209], v[194:195], 0, v[172:173]
	v_lshl_add_u64 v[210:211], v[194:195], 0, v[174:175]
	v_lshl_add_u64 v[212:213], v[194:195], 0, v[176:177]
	v_lshl_add_u64 v[214:215], v[194:195], 0, v[178:179]
	v_lshl_add_u64 v[216:217], v[194:195], 0, v[180:181]
	v_lshl_add_u64 v[220:221], v[194:195], 0, v[182:183]
	v_lshl_add_u64 v[222:223], v[194:195], 0, v[184:185]
	global_load_dwordx4 v[160:163], v[160:161], off nt
	v_lshl_add_u64 v[238:239], v[194:195], 0, v[186:187]
	v_lshl_add_u64 v[240:241], v[194:195], 0, v[188:189]
	v_lshl_add_u64 v[242:243], v[194:195], 0, v[190:191]
	v_lshl_add_u64 v[244:245], v[194:195], 0, v[192:193]
	global_load_dwordx4 v[164:167], v[200:201], off nt
	global_load_dwordx4 v[168:171], v[202:203], off nt
	global_load_dwordx4 v[172:175], v[204:205], off nt
	global_load_dwordx4 v[176:179], v[206:207], off nt
	global_load_dwordx4 v[180:183], v[208:209], off nt
	global_load_dwordx4 v[184:187], v[210:211], off nt
	global_load_dwordx4 v[188:191], v[212:213], off nt
	global_load_dwordx4 v[192:195], v[214:215], off nt
	global_load_dwordx4 v[196:199], v[216:217], off nt
	global_load_dwordx4 v[200:203], v[220:221], off nt
	global_load_dwordx4 v[204:207], v[222:223], off nt
	global_load_dwordx4 v[208:211], v[238:239], off nt
	s_nop 0
	global_load_dwordx4 v[212:215], v[240:241], off nt
	global_load_dwordx4 v[216:219], v[242:243], off nt
	global_load_dwordx4 v[220:223], v[244:245], off nt
	s_waitcnt vmcnt(16)
	s_branch .Lmy_cv_wr

.Lmy_cv_wr:
	v_ashrrev_i32_e32 v5, 31, v4
	v_ashrrev_i32_e32 v7, 31, v6
	v_lshl_add_u64 v[4:5], v[4:5], 1, v[2:3]
	v_lshlrev_b64 v[122:123], 14, v[6:7]
	v_add_u32_e32 v110, 4, v6
	v_lshl_add_u64 v[122:123], v[4:5], 0, v[122:123]
	v_ashrrev_i32_e32 v111, 31, v110
	v_lshlrev_b64 v[110:111], 14, v[110:111]
	v_add_u32_e32 v112, 8, v6
	v_lshl_add_u64 v[110:111], v[4:5], 0, v[110:111]
	v_ashrrev_i32_e32 v113, 31, v112
	v_lshlrev_b64 v[112:113], 14, v[112:113]
	v_add_u32_e32 v114, 12, v6
	v_lshl_add_u64 v[112:113], v[4:5], 0, v[112:113]
	ds_write2_b32 v13, v46, v47 offset1:1
	ds_write2_b32 v13, v48, v49 offset0:2 offset1:3
	ds_write2_b32 v14, v50, v51 offset1:1
	ds_write2_b32 v15, v52, v53 offset1:1
	ds_write2_b32 v16, v54, v55 offset1:1
	ds_write2_b32 v17, v56, v57 offset1:1
	ds_write2_b32 v18, v58, v59 offset1:1
	ds_write2_b32 v19, v60, v61 offset1:1
	ds_write2_b32 v20, v62, v63 offset1:1
	ds_write2_b32 v21, v64, v65 offset1:1
	ds_write2_b32 v22, v66, v67 offset1:1
	ds_write2_b32 v23, v68, v69 offset1:1
	ds_write2_b32 v24, v70, v71 offset1:1
	ds_write2_b32 v25, v72, v73 offset1:1
	ds_write2_b32 v26, v74, v75 offset1:1
	ds_write2_b32 v27, v76, v77 offset1:1
	ds_write2_b32 v28, v78, v79 offset1:1
	ds_write2_b32 v29, v80, v81 offset1:1
	ds_write2_b32 v30, v82, v83 offset1:1
	ds_write2_b32 v31, v84, v85 offset1:1
	ds_write2_b32 v32, v86, v87 offset1:1
	ds_write2_b32 v33, v88, v89 offset1:1
	ds_write2_b32 v34, v90, v91 offset1:1
	ds_write2_b32 v35, v92, v93 offset1:1
	ds_write2_b32 v36, v94, v95 offset1:1
	ds_write2_b32 v37, v96, v97 offset1:1
	ds_write2_b32 v38, v98, v99 offset1:1
	ds_write2_b32 v39, v100, v101 offset1:1
	ds_write2_b32 v40, v102, v103 offset1:1
	ds_write2_b32 v41, v104, v105 offset1:1
	ds_write2_b32 v42, v106, v107 offset1:1
	ds_write2_b32 v43, v108, v109 offset1:1
	s_waitcnt lgkmcnt(0)
	ds_read2_b32 v[46:47], v11 offset1:65
	s_waitcnt lgkmcnt(0)
	v_cvt_pk_bf16_f32 v46, v46, v47
	ds_read2_b32 v[48:49], v11 offset0:130 offset1:195
	s_waitcnt lgkmcnt(0)
	v_cvt_pk_bf16_f32 v47, v48, v49
	ds_read2_b32 v[48:49], v44 offset0:4 offset1:69
	s_waitcnt lgkmcnt(0)
	v_cvt_pk_bf16_f32 v48, v48, v49
	ds_read2_b32 v[50:51], v44 offset0:134 offset1:199
	s_waitcnt lgkmcnt(0)
	v_cvt_pk_bf16_f32 v49, v50, v51
	ds_read2_b32 v[50:51], v11 offset0:8 offset1:73
	global_store_dwordx4 v[122:123], v[46:49], off
	v_ashrrev_i32_e32 v115, 31, v114
	v_lshlrev_b64 v[114:115], 14, v[114:115]
	s_waitcnt lgkmcnt(0)
	v_cvt_pk_bf16_f32 v46, v50, v51
	ds_read2_b32 v[48:49], v11 offset0:138 offset1:203
	s_waitcnt lgkmcnt(0)
	v_cvt_pk_bf16_f32 v47, v48, v49
	ds_read2_b32 v[48:49], v44 offset0:12 offset1:77
	s_waitcnt lgkmcnt(0)
	v_cvt_pk_bf16_f32 v48, v48, v49
	ds_read2_b32 v[50:51], v44 offset0:142 offset1:207
	s_waitcnt lgkmcnt(0)
	v_cvt_pk_bf16_f32 v49, v50, v51
	ds_read2_b32 v[50:51], v11 offset0:16 offset1:81
	global_store_dwordx4 v[110:111], v[46:49], off
	v_add_u32_e32 v116, 32, v6
	v_lshl_add_u64 v[114:115], v[4:5], 0, v[114:115]
	s_waitcnt lgkmcnt(0)
	v_cvt_pk_bf16_f32 v46, v50, v51
	ds_read2_b32 v[48:49], v11 offset0:146 offset1:211
	s_waitcnt lgkmcnt(0)
	v_cvt_pk_bf16_f32 v47, v48, v49
	ds_read2_b32 v[48:49], v44 offset0:20 offset1:85
	s_waitcnt lgkmcnt(0)
	v_cvt_pk_bf16_f32 v48, v48, v49
	ds_read2_b32 v[50:51], v44 offset0:150 offset1:215
	s_waitcnt lgkmcnt(0)
	v_cvt_pk_bf16_f32 v49, v50, v51
	ds_read2_b32 v[50:51], v11 offset0:24 offset1:89
	global_store_dwordx4 v[112:113], v[46:49], off
	v_ashrrev_i32_e32 v117, 31, v116
	v_lshlrev_b64 v[116:117], 14, v[116:117]
	s_waitcnt lgkmcnt(0)
	v_cvt_pk_bf16_f32 v46, v50, v51
	ds_read2_b32 v[48:49], v11 offset0:154 offset1:219
	s_waitcnt lgkmcnt(0)
	v_cvt_pk_bf16_f32 v47, v48, v49
	ds_read2_b32 v[48:49], v44 offset0:28 offset1:93
	s_waitcnt lgkmcnt(0)
	v_cvt_pk_bf16_f32 v48, v48, v49
	ds_read2_b32 v[50:51], v44 offset0:158 offset1:223
	s_waitcnt lgkmcnt(0)
	v_cvt_pk_bf16_f32 v49, v50, v51
	ds_read2_b32 v[50:51], v11 offset0:32 offset1:97
	global_store_dwordx4 v[114:115], v[46:49], off
	v_add_u32_e32 v118, 36, v6
	v_lshl_add_u64 v[116:117], v[4:5], 0, v[116:117]
	s_waitcnt lgkmcnt(0)
	v_cvt_pk_bf16_f32 v46, v50, v51
	ds_read2_b32 v[48:49], v11 offset0:162 offset1:227
	s_waitcnt lgkmcnt(0)
	v_cvt_pk_bf16_f32 v47, v48, v49
	ds_read2_b32 v[48:49], v44 offset0:36 offset1:101
	s_waitcnt lgkmcnt(0)
	v_cvt_pk_bf16_f32 v48, v48, v49
	ds_read2_b32 v[50:51], v44 offset0:166 offset1:231
	s_waitcnt lgkmcnt(0)
	v_cvt_pk_bf16_f32 v49, v50, v51
	v_ashrrev_i32_e32 v119, 31, v118
	ds_read2_b32 v[50:51], v11 offset0:40 offset1:105
	global_store_dwordx4 v[116:117], v[46:49], off
	v_lshlrev_b64 v[118:119], 14, v[118:119]
	v_add_u32_e32 v120, 40, v6
	s_waitcnt lgkmcnt(0)
	v_cvt_pk_bf16_f32 v46, v50, v51
	ds_read2_b32 v[48:49], v11 offset0:170 offset1:235
	s_waitcnt lgkmcnt(0)
	v_cvt_pk_bf16_f32 v47, v48, v49
	ds_read2_b32 v[48:49], v44 offset0:44 offset1:109
	v_lshl_add_u64 v[118:119], v[4:5], 0, v[118:119]
	s_waitcnt lgkmcnt(0)
	v_cvt_pk_bf16_f32 v48, v48, v49
	ds_read2_b32 v[50:51], v44 offset0:174 offset1:239
	s_waitcnt lgkmcnt(0)
	v_cvt_pk_bf16_f32 v49, v50, v51
	v_ashrrev_i32_e32 v121, 31, v120
	ds_read2_b32 v[50:51], v11 offset0:48 offset1:113
	global_store_dwordx4 v[118:119], v[46:49], off
	v_lshlrev_b64 v[120:121], 14, v[120:121]
	v_add_u32_e32 v6, 44, v6
	s_waitcnt lgkmcnt(0)
	v_cvt_pk_bf16_f32 v46, v50, v51
	ds_read2_b32 v[48:49], v11 offset0:178 offset1:243
	s_waitcnt lgkmcnt(0)
	v_cvt_pk_bf16_f32 v47, v48, v49
	ds_read2_b32 v[48:49], v44 offset0:52 offset1:117
	v_lshl_add_u64 v[120:121], v[4:5], 0, v[120:121]
	s_waitcnt lgkmcnt(0)
	v_cvt_pk_bf16_f32 v48, v48, v49
	ds_read2_b32 v[50:51], v44 offset0:182 offset1:247
	s_waitcnt lgkmcnt(0)
	v_cvt_pk_bf16_f32 v49, v50, v51
	v_ashrrev_i32_e32 v7, 31, v6
	ds_read2_b32 v[50:51], v11 offset0:56 offset1:121
	global_store_dwordx4 v[120:121], v[46:49], off
	v_lshlrev_b64 v[6:7], 14, v[6:7]
	v_lshl_add_u64 v[4:5], v[4:5], 0, v[6:7]
	s_waitcnt lgkmcnt(0)
	v_cvt_pk_bf16_f32 v46, v50, v51
	ds_read2_b32 v[48:49], v11 offset0:186 offset1:251
	s_waitcnt lgkmcnt(0)
	v_cvt_pk_bf16_f32 v47, v48, v49
	ds_read2_b32 v[48:49], v44 offset0:60 offset1:125
	s_waitcnt lgkmcnt(0)
	v_cvt_pk_bf16_f32 v48, v48, v49
	ds_read2_b32 v[50:51], v44 offset0:190 offset1:255
	s_waitcnt lgkmcnt(0)
	v_cvt_pk_bf16_f32 v49, v50, v51
	global_store_dwordx4 v[4:5], v[46:49], off
	s_waitcnt lgkmcnt(0)
	v_cmp_gt_i32_e32 vcc, s5, v132
	s_cbranch_vccz .LBB0_1257
	s_waitcnt vmcnt(8)
	v_mov_b32_e32 v46, v160
	v_mov_b32_e32 v47, v161
	v_mov_b32_e32 v48, v162
	v_mov_b32_e32 v49, v163
	v_mov_b32_e32 v50, v164
	v_mov_b32_e32 v51, v165
	v_mov_b32_e32 v52, v166
	v_mov_b32_e32 v53, v167
	v_mov_b32_e32 v54, v168
	v_mov_b32_e32 v55, v169
	v_mov_b32_e32 v56, v170
	v_mov_b32_e32 v57, v171
	v_mov_b32_e32 v58, v172
	v_mov_b32_e32 v59, v173
	v_mov_b32_e32 v60, v174
	v_mov_b32_e32 v61, v175
	v_mov_b32_e32 v62, v176
	v_mov_b32_e32 v63, v177
	v_mov_b32_e32 v64, v178
	v_mov_b32_e32 v65, v179
	v_mov_b32_e32 v66, v180
	v_mov_b32_e32 v67, v181
	v_mov_b32_e32 v68, v182
	v_mov_b32_e32 v69, v183
	v_mov_b32_e32 v70, v184
	v_mov_b32_e32 v71, v185
	v_mov_b32_e32 v72, v186
	v_mov_b32_e32 v73, v187
	v_mov_b32_e32 v74, v188
	v_mov_b32_e32 v75, v189
	v_mov_b32_e32 v76, v190
	v_mov_b32_e32 v77, v191
	v_mov_b32_e32 v78, v192
	v_mov_b32_e32 v79, v193
	v_mov_b32_e32 v80, v194
	v_mov_b32_e32 v81, v195
	v_mov_b32_e32 v82, v196
	v_mov_b32_e32 v83, v197
	v_mov_b32_e32 v84, v198
	v_mov_b32_e32 v85, v199
	v_mov_b32_e32 v86, v200
	v_mov_b32_e32 v87, v201
	v_mov_b32_e32 v88, v202
	v_mov_b32_e32 v89, v203
	v_mov_b32_e32 v90, v204
	v_mov_b32_e32 v91, v205
	v_mov_b32_e32 v92, v206
	v_mov_b32_e32 v93, v207
	v_mov_b32_e32 v94, v208
	v_mov_b32_e32 v95, v209
	v_mov_b32_e32 v96, v210
	v_mov_b32_e32 v97, v211
	v_mov_b32_e32 v98, v212
	v_mov_b32_e32 v99, v213
	v_mov_b32_e32 v100, v214
	v_mov_b32_e32 v101, v215
	v_mov_b32_e32 v102, v216
	v_mov_b32_e32 v103, v217
	v_mov_b32_e32 v104, v218
	v_mov_b32_e32 v105, v219
	v_mov_b32_e32 v106, v220
	v_mov_b32_e32 v107, v221
	v_mov_b32_e32 v108, v222
	v_mov_b32_e32 v109, v223
	v_mov_b32_e32 v4, v246
	v_mov_b32_e32 v6, v248
	v_mov_b32_e32 v8, v132
	v_mov_b32_e32 v12, v133
	s_branch .Lmy_cv_loop

.LBB0_1508:
	v_lshl_add_u32 v144, s28, 8, v146
	v_and_b32_e32 v145, 12, v148
	v_add_u32_e32 v145, v148, v145
	v_lshl_or_b32 v142, s53, 8, v145
	v_ashrrev_i32_e32 v145, 31, v144
	v_ashrrev_i32_e32 v143, 31, v142
	v_lshlrev_b64 v[140:141], 11, v[144:145]
	v_lshl_add_u64 v[140:141], v[140:141], 0, v[142:143]
	v_lshl_add_u64 v[152:153], v[140:141], 1, s[4:5]
	v_lshl_add_u64 v[156:157], v[140:141], 2, s[82:83]
	global_load_dwordx4 v[220:223], v[152:153], off
	global_load_dwordx4 v[224:227], v[152:153], off offset:256
	v_mov_b64_e32 v[154:155], v[152:153]
	v_mov_b64_e32 v[158:159], v[156:157]
	s_mov_b32 s90, 0x10000
	s_mov_b32 s91, 0
	s_mov_b32 s92, 0x80000
	s_mov_b32 s93, 0
	s_mov_b32 s94, 0x20000
	s_mov_b32 s95, 0
	s_mov_b32 s96, 0x100000
	s_mov_b32 s97, 0
	v_lshl_add_u64 v[152:153], v[152:153], 0, s[90:91]
	global_load_dwordx4 v[228:231], v[152:153], off
	global_load_dwordx4 v[232:235], v[152:153], off offset:256
	s_waitcnt vmcnt(2)
	v_lshlrev_b32_e32 v140, 16, v220
	v_and_b32_e32 v141, 0xffff0000, v220
	v_lshlrev_b32_e32 v142, 16, v221
	v_and_b32_e32 v143, 0xffff0000, v221
	v_pk_add_f32 v[236:237], v[124:125], v[140:141]
	v_pk_add_f32 v[238:239], v[126:127], v[142:143]
	global_store_dwordx4 v[156:157], v[236:239], off sc0 sc1 nt
	v_lshlrev_b32_e32 v140, 16, v222
	v_and_b32_e32 v141, 0xffff0000, v222
	v_lshlrev_b32_e32 v142, 16, v223
	v_and_b32_e32 v143, 0xffff0000, v223
	v_pk_add_f32 v[240:241], v[120:121], v[140:141]
	v_pk_add_f32 v[242:243], v[122:123], v[142:143]
	global_store_dwordx4 v[156:157], v[240:243], off offset:16 sc0 sc1 nt
	v_lshlrev_b32_e32 v140, 16, v224
	v_and_b32_e32 v141, 0xffff0000, v224
	v_lshlrev_b32_e32 v142, 16, v225
	v_and_b32_e32 v143, 0xffff0000, v225
	v_pk_add_f32 v[244:245], v[116:117], v[140:141]
	v_pk_add_f32 v[246:247], v[118:119], v[142:143]
	global_store_dwordx4 v[156:157], v[244:247], off offset:512 sc0 sc1 nt
	v_lshlrev_b32_e32 v140, 16, v226
	v_and_b32_e32 v141, 0xffff0000, v226
	v_lshlrev_b32_e32 v142, 16, v227
	v_and_b32_e32 v143, 0xffff0000, v227
	v_pk_add_f32 v[248:249], v[108:109], v[140:141]
	v_pk_add_f32 v[250:251], v[110:111], v[142:143]
	global_store_dwordx4 v[156:157], v[248:251], off offset:528 sc0 sc1 nt
	v_lshl_add_u64 v[156:157], v[156:157], 0, s[94:95]
	v_lshl_add_u64 v[152:153], v[152:153], 0, s[90:91]
	global_load_dwordx4 v[220:223], v[152:153], off
	global_load_dwordx4 v[224:227], v[152:153], off offset:256
	s_waitcnt vmcnt(6)
	v_lshlrev_b32_e32 v140, 16, v228
	v_and_b32_e32 v141, 0xffff0000, v228
	v_lshlrev_b32_e32 v142, 16, v229
	v_and_b32_e32 v143, 0xffff0000, v229
	v_pk_add_f32 v[236:237], v[112:113], v[140:141]
	v_pk_add_f32 v[238:239], v[114:115], v[142:143]
	global_store_dwordx4 v[156:157], v[236:239], off sc0 sc1 nt
	v_lshlrev_b32_e32 v140, 16, v230
	v_and_b32_e32 v141, 0xffff0000, v230
	v_lshlrev_b32_e32 v142, 16, v231
	v_and_b32_e32 v143, 0xffff0000, v231
	v_pk_add_f32 v[240:241], v[104:105], v[140:141]
	v_pk_add_f32 v[242:243], v[106:107], v[142:143]
	global_store_dwordx4 v[156:157], v[240:243], off offset:16 sc0 sc1 nt
	v_lshlrev_b32_e32 v140, 16, v232
	v_and_b32_e32 v141, 0xffff0000, v232
	v_lshlrev_b32_e32 v142, 16, v233
	v_and_b32_e32 v143, 0xffff0000, v233
	v_pk_add_f32 v[244:245], v[100:101], v[140:141]
	v_pk_add_f32 v[246:247], v[102:103], v[142:143]
	global_store_dwordx4 v[156:157], v[244:247], off offset:512 sc0 sc1 nt
	v_lshlrev_b32_e32 v140, 16, v234
	v_and_b32_e32 v141, 0xffff0000, v234
	v_lshlrev_b32_e32 v142, 16, v235
	v_and_b32_e32 v143, 0xffff0000, v235
	v_pk_add_f32 v[248:249], v[92:93], v[140:141]
	v_pk_add_f32 v[250:251], v[94:95], v[142:143]
	global_store_dwordx4 v[156:157], v[248:251], off offset:528 sc0 sc1 nt
	v_lshl_add_u64 v[156:157], v[156:157], 0, s[94:95]
	v_lshl_add_u64 v[152:153], v[152:153], 0, s[90:91]
	global_load_dwordx4 v[228:231], v[152:153], off
	global_load_dwordx4 v[232:235], v[152:153], off offset:256
	s_waitcnt vmcnt(6)
	v_lshlrev_b32_e32 v140, 16, v220
	v_and_b32_e32 v141, 0xffff0000, v220
	v_lshlrev_b32_e32 v142, 16, v221
	v_and_b32_e32 v143, 0xffff0000, v221
	v_pk_add_f32 v[236:237], v[96:97], v[140:141]
	v_pk_add_f32 v[238:239], v[98:99], v[142:143]
	global_store_dwordx4 v[156:157], v[236:239], off sc0 sc1 nt
	v_lshlrev_b32_e32 v140, 16, v222
	v_and_b32_e32 v141, 0xffff0000, v222
	v_lshlrev_b32_e32 v142, 16, v223
	v_and_b32_e32 v143, 0xffff0000, v223
	v_pk_add_f32 v[240:241], v[88:89], v[140:141]
	v_pk_add_f32 v[242:243], v[90:91], v[142:143]
	global_store_dwordx4 v[156:157], v[240:243], off offset:16 sc0 sc1 nt
	v_lshlrev_b32_e32 v140, 16, v224
	v_and_b32_e32 v141, 0xffff0000, v224
	v_lshlrev_b32_e32 v142, 16, v225
	v_and_b32_e32 v143, 0xffff0000, v225
	v_pk_add_f32 v[244:245], v[84:85], v[140:141]
	v_pk_add_f32 v[246:247], v[86:87], v[142:143]
	global_store_dwordx4 v[156:157], v[244:247], off offset:512 sc0 sc1 nt
	v_lshlrev_b32_e32 v140, 16, v226
	v_and_b32_e32 v141, 0xffff0000, v226
	v_lshlrev_b32_e32 v142, 16, v227
	v_and_b32_e32 v143, 0xffff0000, v227
	v_pk_add_f32 v[248:249], v[76:77], v[140:141]
	v_pk_add_f32 v[250:251], v[78:79], v[142:143]
	global_store_dwordx4 v[156:157], v[248:251], off offset:528 sc0 sc1 nt
	v_lshl_add_u64 v[156:157], v[156:157], 0, s[94:95]
	v_lshl_add_u64 v[152:153], v[154:155], 0, s[92:93]
	global_load_dwordx4 v[220:223], v[152:153], off
	global_load_dwordx4 v[224:227], v[152:153], off offset:256
	s_waitcnt vmcnt(6)
	v_lshlrev_b32_e32 v140, 16, v228
	v_and_b32_e32 v141, 0xffff0000, v228
	v_lshlrev_b32_e32 v142, 16, v229
	v_and_b32_e32 v143, 0xffff0000, v229
	v_pk_add_f32 v[236:237], v[80:81], v[140:141]
	v_pk_add_f32 v[238:239], v[82:83], v[142:143]
	global_store_dwordx4 v[156:157], v[236:239], off sc0 sc1 nt
	v_lshlrev_b32_e32 v140, 16, v230
	v_and_b32_e32 v141, 0xffff0000, v230
	v_lshlrev_b32_e32 v142, 16, v231
	v_and_b32_e32 v143, 0xffff0000, v231
	v_pk_add_f32 v[240:241], v[72:73], v[140:141]
	v_pk_add_f32 v[242:243], v[74:75], v[142:143]
	global_store_dwordx4 v[156:157], v[240:243], off offset:16 sc0 sc1 nt
	v_lshlrev_b32_e32 v140, 16, v232
	v_and_b32_e32 v141, 0xffff0000, v232
	v_lshlrev_b32_e32 v142, 16, v233
	v_and_b32_e32 v143, 0xffff0000, v233
	v_pk_add_f32 v[244:245], v[68:69], v[140:141]
	v_pk_add_f32 v[246:247], v[70:71], v[142:143]
	global_store_dwordx4 v[156:157], v[244:247], off offset:512 sc0 sc1 nt
	v_lshlrev_b32_e32 v140, 16, v234
	v_and_b32_e32 v141, 0xffff0000, v234
	v_lshlrev_b32_e32 v142, 16, v235
	v_and_b32_e32 v143, 0xffff0000, v235
	v_pk_add_f32 v[248:249], v[64:65], v[140:141]
	v_pk_add_f32 v[250:251], v[66:67], v[142:143]
	global_store_dwordx4 v[156:157], v[248:251], off offset:528 sc0 sc1 nt
	v_lshl_add_u64 v[156:157], v[158:159], 0, s[96:97]
	v_lshl_add_u64 v[152:153], v[152:153], 0, s[90:91]
	global_load_dwordx4 v[228:231], v[152:153], off
	global_load_dwordx4 v[232:235], v[152:153], off offset:256
	s_waitcnt vmcnt(6)
	v_lshlrev_b32_e32 v140, 16, v220
	v_and_b32_e32 v141, 0xffff0000, v220
	v_lshlrev_b32_e32 v142, 16, v221
	v_and_b32_e32 v143, 0xffff0000, v221
	v_pk_add_f32 v[236:237], v[60:61], v[140:141]
	v_pk_add_f32 v[238:239], v[62:63], v[142:143]
	global_store_dwordx4 v[156:157], v[236:239], off sc0 sc1 nt
	v_lshlrev_b32_e32 v140, 16, v222
	v_and_b32_e32 v141, 0xffff0000, v222
	v_lshlrev_b32_e32 v142, 16, v223
	v_and_b32_e32 v143, 0xffff0000, v223
	v_pk_add_f32 v[240:241], v[56:57], v[140:141]
	v_pk_add_f32 v[242:243], v[58:59], v[142:143]
	global_store_dwordx4 v[156:157], v[240:243], off offset:16 sc0 sc1 nt
	v_lshlrev_b32_e32 v140, 16, v224
	v_and_b32_e32 v141, 0xffff0000, v224
	v_lshlrev_b32_e32 v142, 16, v225
	v_and_b32_e32 v143, 0xffff0000, v225
	v_pk_add_f32 v[244:245], v[52:53], v[140:141]
	v_pk_add_f32 v[246:247], v[54:55], v[142:143]
	global_store_dwordx4 v[156:157], v[244:247], off offset:512 sc0 sc1 nt
	v_lshlrev_b32_e32 v140, 16, v226
	v_and_b32_e32 v141, 0xffff0000, v226
	v_lshlrev_b32_e32 v142, 16, v227
	v_and_b32_e32 v143, 0xffff0000, v227
	v_pk_add_f32 v[248:249], v[44:45], v[140:141]
	v_pk_add_f32 v[250:251], v[46:47], v[142:143]
	global_store_dwordx4 v[156:157], v[248:251], off offset:528 sc0 sc1 nt
	v_lshl_add_u64 v[156:157], v[156:157], 0, s[94:95]
	v_lshl_add_u64 v[152:153], v[152:153], 0, s[90:91]
	global_load_dwordx4 v[220:223], v[152:153], off
	global_load_dwordx4 v[224:227], v[152:153], off offset:256
	s_waitcnt vmcnt(6)
	v_lshlrev_b32_e32 v140, 16, v228
	v_and_b32_e32 v141, 0xffff0000, v228
	v_lshlrev_b32_e32 v142, 16, v229
	v_and_b32_e32 v143, 0xffff0000, v229
	v_pk_add_f32 v[236:237], v[48:49], v[140:141]
	v_pk_add_f32 v[238:239], v[50:51], v[142:143]
	global_store_dwordx4 v[156:157], v[236:239], off sc0 sc1 nt
	v_lshlrev_b32_e32 v140, 16, v230
	v_and_b32_e32 v141, 0xffff0000, v230
	v_lshlrev_b32_e32 v142, 16, v231
	v_and_b32_e32 v143, 0xffff0000, v231
	v_pk_add_f32 v[240:241], v[40:41], v[140:141]
	v_pk_add_f32 v[242:243], v[42:43], v[142:143]
	global_store_dwordx4 v[156:157], v[240:243], off offset:16 sc0 sc1 nt
	v_lshlrev_b32_e32 v140, 16, v232
	v_and_b32_e32 v141, 0xffff0000, v232
	v_lshlrev_b32_e32 v142, 16, v233
	v_and_b32_e32 v143, 0xffff0000, v233
	v_pk_add_f32 v[244:245], v[36:37], v[140:141]
	v_pk_add_f32 v[246:247], v[38:39], v[142:143]
	global_store_dwordx4 v[156:157], v[244:247], off offset:512 sc0 sc1 nt
	v_lshlrev_b32_e32 v140, 16, v234
	v_and_b32_e32 v141, 0xffff0000, v234
	v_lshlrev_b32_e32 v142, 16, v235
	v_and_b32_e32 v143, 0xffff0000, v235
	v_pk_add_f32 v[248:249], v[28:29], v[140:141]
	v_pk_add_f32 v[250:251], v[30:31], v[142:143]
	global_store_dwordx4 v[156:157], v[248:251], off offset:528 sc0 sc1 nt
	v_lshl_add_u64 v[156:157], v[156:157], 0, s[94:95]
	v_lshl_add_u64 v[152:153], v[152:153], 0, s[90:91]
	global_load_dwordx4 v[228:231], v[152:153], off
	global_load_dwordx4 v[232:235], v[152:153], off offset:256
	s_waitcnt vmcnt(6)
	v_lshlrev_b32_e32 v140, 16, v220
	v_and_b32_e32 v141, 0xffff0000, v220
	v_lshlrev_b32_e32 v142, 16, v221
	v_and_b32_e32 v143, 0xffff0000, v221
	v_pk_add_f32 v[236:237], v[32:33], v[140:141]
	v_pk_add_f32 v[238:239], v[34:35], v[142:143]
	global_store_dwordx4 v[156:157], v[236:239], off sc0 sc1 nt
	v_lshlrev_b32_e32 v140, 16, v222
	v_and_b32_e32 v141, 0xffff0000, v222
	v_lshlrev_b32_e32 v142, 16, v223
	v_and_b32_e32 v143, 0xffff0000, v223
	v_pk_add_f32 v[240:241], v[24:25], v[140:141]
	v_pk_add_f32 v[242:243], v[26:27], v[142:143]
	global_store_dwordx4 v[156:157], v[240:243], off offset:16 sc0 sc1 nt
	v_lshlrev_b32_e32 v140, 16, v224
	v_and_b32_e32 v141, 0xffff0000, v224
	v_lshlrev_b32_e32 v142, 16, v225
	v_and_b32_e32 v143, 0xffff0000, v225
	v_pk_add_f32 v[244:245], v[20:21], v[140:141]
	v_pk_add_f32 v[246:247], v[22:23], v[142:143]
	global_store_dwordx4 v[156:157], v[244:247], off offset:512 sc0 sc1 nt
	v_lshlrev_b32_e32 v140, 16, v226
	v_and_b32_e32 v141, 0xffff0000, v226
	v_lshlrev_b32_e32 v142, 16, v227
	v_and_b32_e32 v143, 0xffff0000, v227
	v_pk_add_f32 v[248:249], v[12:13], v[140:141]
	v_pk_add_f32 v[250:251], v[14:15], v[142:143]
	global_store_dwordx4 v[156:157], v[248:251], off offset:528 sc0 sc1 nt
	v_lshl_add_u64 v[156:157], v[156:157], 0, s[94:95]
	s_waitcnt vmcnt(4)
	v_lshlrev_b32_e32 v140, 16, v228
	v_and_b32_e32 v141, 0xffff0000, v228
	v_lshlrev_b32_e32 v142, 16, v229
	v_and_b32_e32 v143, 0xffff0000, v229
	v_pk_add_f32 v[236:237], v[16:17], v[140:141]
	v_pk_add_f32 v[238:239], v[18:19], v[142:143]
	global_store_dwordx4 v[156:157], v[236:239], off sc0 sc1 nt
	v_lshlrev_b32_e32 v140, 16, v230
	v_and_b32_e32 v141, 0xffff0000, v230
	v_lshlrev_b32_e32 v142, 16, v231
	v_and_b32_e32 v143, 0xffff0000, v231
	v_pk_add_f32 v[240:241], v[8:9], v[140:141]
	v_pk_add_f32 v[242:243], v[10:11], v[142:143]
	global_store_dwordx4 v[156:157], v[240:243], off offset:16 sc0 sc1 nt
	v_lshlrev_b32_e32 v140, 16, v232
	v_and_b32_e32 v141, 0xffff0000, v232
	v_lshlrev_b32_e32 v142, 16, v233
	v_and_b32_e32 v143, 0xffff0000, v233
	v_pk_add_f32 v[244:245], v[4:5], v[140:141]
	v_pk_add_f32 v[246:247], v[6:7], v[142:143]
	global_store_dwordx4 v[156:157], v[244:247], off offset:512 sc0 sc1 nt
	v_lshlrev_b32_e32 v140, 16, v234
	v_and_b32_e32 v141, 0xffff0000, v234
	v_lshlrev_b32_e32 v142, 16, v235
	v_and_b32_e32 v143, 0xffff0000, v235
	v_pk_add_f32 v[248:249], v[0:1], v[140:141]
	v_pk_add_f32 v[250:251], v[2:3], v[142:143]
	global_store_dwordx4 v[156:157], v[248:251], off offset:528 sc0 sc1 nt
	s_andn2_b64 vcc, exec, s[0:1]
	s_mov_b64 s[0:1], -1
	s_cbranch_vccnz .LBB0_1497
	s_andn2_b64 vcc, exec, s[2:3]
	s_cbranch_vccnz .LBB0_1496
	s_barrier
	s_branch .LBB0_1496
